# attention unit hand-off: the overflow vote rides on the staging barrier, and the CU's first dual unit prefetches the next unit's first K/V tile into the idle ring slot during its epilogue (staging mov
# speedup vs baseline: 1.0120x; 1.0006x over previous
; template <int VAR>
; __device__ __forceinline__ void attn_unit(const Args& a, int l, int b, int h, int qrow0  , bool ctxu, const bf16* Z, bf16* Y, LAS unsigned char* lds) {
;     ...
;     float lam, omli;
;     { float s1 = 0.f, s2 = 0.f;
;       for (int i = 0; i < 32; ++i) { s1 += a.lam_q1[l * 32 + i] * a.lam_k1[l * 32 + i]; s2 += a.lam_q2[l * 32 + i] * a.lam_k2[l * 32 + i]; }
;       const float li = 0.8f - 0.6f * expf(-0.3f * (float)l); lam = expf(s1) - expf(s2) + li; omli = 1.f - li; }
.LBB0_426:
	v_readlane_b32 s8, v254, 46
	v_readlane_b32 s9, v254, 47
	s_andn2_b64 vcc, exec, s[8:9]
	s_cbranch_vccnz .LBB0_464
	v_cvt_f32_u32_e32 v0, s68
	s_mov_b32 s8, 0x3fb8aa3b
	s_lshl_b32 s72, s68, 5
	v_readlane_b32 s36, v252, 27
	v_mul_f32_e32 v0, 0xbe99999a, v0
	v_mul_f32_e32 v1, 0x3fb8aa3b, v0
	v_fma_f32 v2, v0, s8, -v1
	v_rndne_f32_e32 v3, v1
	v_fmac_f32_e32 v2, 0x32a5705f, v0
	v_sub_f32_e32 v1, v1, v3
	v_add_f32_e32 v1, v1, v2
	v_cvt_i32_f32_e32 v3, v3
	v_exp_f32_e32 v1, v1
	s_mov_b32 s8, 0xc2ce8ed0
	v_cmp_ngt_f32_e32 vcc, s8, v0
	s_mov_b32 s8, 0x42b17218
	v_ldexp_f32 v1, v1, v3
	v_cndmask_b32_e32 v1, 0, v1, vcc
	v_cmp_nlt_f32_e32 vcc, s8, v0
	s_lshl_b64 s[8:9], s[72:73], 2
	v_readlane_b32 s40, v252, 31
	v_readlane_b32 s46, v252, 37
	v_readlane_b32 s41, v252, 32
	v_readlane_b32 s47, v252, 38
	s_add_u32 s40, s46, s8
	v_readlane_b32 s42, v252, 33
	v_readlane_b32 s48, v252, 39
	s_addc_u32 s41, s47, s9
	v_readlane_b32 s43, v252, 34
	v_readlane_b32 s49, v252, 40
	s_add_u32 s42, s48, s8
	v_readlane_b32 s44, v252, 35
	v_readlane_b32 s50, v252, 41
	s_addc_u32 s43, s49, s9
	v_readlane_b32 s45, v252, 36
	v_readlane_b32 s51, v252, 42
	s_add_u32 s44, s50, s8
	v_cndmask_b32_e32 v0, v245, v1, vcc
	s_addc_u32 s45, s51, s9
	v_readlane_b32 s76, v252, 43
	v_fmamk_f32 v221, v0, 0xbf19999a, v220
	v_readlane_b32 s77, v252, 44
	s_add_u32 s46, s76, s8
	v_sub_f32_e32 v226, 1.0, v221
	s_addc_u32 s47, s77, s9
	s_lshl_b32 s58, s68, 6
	s_mov_b32 s59, 0
	global_load_dwordx4 v[0:3], v217, s[40:41]
	global_load_dwordx4 v[4:7], v217, s[40:41] offset:16
	global_load_dwordx4 v[8:11], v217, s[40:41] offset:32
	global_load_dwordx4 v[12:15], v217, s[40:41] offset:48
	global_load_dwordx4 v[16:19], v217, s[40:41] offset:64
	global_load_dwordx4 v[20:23], v217, s[40:41] offset:80
	global_load_dwordx4 v[24:27], v217, s[40:41] offset:96
	global_load_dwordx4 v[28:31], v217, s[40:41] offset:112
	global_load_dwordx4 v[32:35], v217, s[42:43]
	global_load_dwordx4 v[36:39], v217, s[42:43] offset:16
	global_load_dwordx4 v[40:43], v217, s[42:43] offset:32
	global_load_dwordx4 v[44:47], v217, s[42:43] offset:48
	global_load_dwordx4 v[48:51], v217, s[42:43] offset:64
	global_load_dwordx4 v[52:55], v217, s[42:43] offset:80
	global_load_dwordx4 v[56:59], v217, s[42:43] offset:96
	global_load_dwordx4 v[60:63], v217, s[42:43] offset:112
	global_load_dwordx4 v[64:67], v217, s[44:45]
	global_load_dwordx4 v[68:71], v217, s[44:45] offset:16
	global_load_dwordx4 v[72:75], v217, s[44:45] offset:32
	global_load_dwordx4 v[76:79], v217, s[44:45] offset:48
	global_load_dwordx4 v[80:83], v217, s[44:45] offset:64
	global_load_dwordx4 v[84:87], v217, s[44:45] offset:80
	global_load_dwordx4 v[88:91], v217, s[44:45] offset:96
	global_load_dwordx4 v[92:95], v217, s[44:45] offset:112
	global_load_dwordx4 v[96:99], v217, s[46:47]
	global_load_dwordx4 v[100:103], v217, s[46:47] offset:16
	global_load_dwordx4 v[104:107], v217, s[46:47] offset:32
	global_load_dwordx4 v[108:111], v217, s[46:47] offset:48
	global_load_dwordx4 v[112:115], v217, s[46:47] offset:64
	global_load_dwordx4 v[116:119], v217, s[46:47] offset:80
	global_load_dwordx4 v[120:123], v217, s[46:47] offset:96
	global_load_dwordx4 v[124:127], v217, s[46:47] offset:112
	s_mov_b32 s50, 0x3fb8aa3b
	s_mov_b32 s51, 0xc2ce8ed0
	s_mov_b32 s93, 0x42b17218
	s_waitcnt vmcnt(0)
	v_fma_f32 v128, v0, v32, 0
	v_fmac_f32_e32 v128, v1, v33
	v_fmac_f32_e32 v128, v2, v34
	v_fmac_f32_e32 v128, v3, v35
	v_fmac_f32_e32 v128, v4, v36
	v_fmac_f32_e32 v128, v5, v37
	v_fmac_f32_e32 v128, v6, v38
	v_fmac_f32_e32 v128, v7, v39
	v_fmac_f32_e32 v128, v8, v40
	v_fmac_f32_e32 v128, v9, v41
	v_fmac_f32_e32 v128, v10, v42
	v_fmac_f32_e32 v128, v11, v43
	v_fmac_f32_e32 v128, v12, v44
	v_fmac_f32_e32 v128, v13, v45
	v_fmac_f32_e32 v128, v14, v46
	v_fmac_f32_e32 v128, v15, v47
	v_fmac_f32_e32 v128, v16, v48
	v_fmac_f32_e32 v128, v17, v49
	v_fmac_f32_e32 v128, v18, v50
	v_fmac_f32_e32 v128, v19, v51
	v_fmac_f32_e32 v128, v20, v52
	v_fmac_f32_e32 v128, v21, v53
	v_fmac_f32_e32 v128, v22, v54
	v_fmac_f32_e32 v128, v23, v55
	v_fmac_f32_e32 v128, v24, v56
	v_fmac_f32_e32 v128, v25, v57
	v_fmac_f32_e32 v128, v26, v58
	v_fmac_f32_e32 v128, v27, v59
	v_fmac_f32_e32 v128, v28, v60
	v_fmac_f32_e32 v128, v29, v61
	v_fmac_f32_e32 v128, v30, v62
	v_fmac_f32_e32 v128, v31, v63
	v_fma_f32 v129, v64, v96, 0
	v_fmac_f32_e32 v129, v65, v97
	v_fmac_f32_e32 v129, v66, v98
	v_fmac_f32_e32 v129, v67, v99
	v_fmac_f32_e32 v129, v68, v100
	v_fmac_f32_e32 v129, v69, v101
	v_fmac_f32_e32 v129, v70, v102
	v_fmac_f32_e32 v129, v71, v103
	v_fmac_f32_e32 v129, v72, v104
	v_fmac_f32_e32 v129, v73, v105
	v_fmac_f32_e32 v129, v74, v106
	v_fmac_f32_e32 v129, v75, v107
	v_fmac_f32_e32 v129, v76, v108
	v_fmac_f32_e32 v129, v77, v109
	v_fmac_f32_e32 v129, v78, v110
	v_fmac_f32_e32 v129, v79, v111
	v_fmac_f32_e32 v129, v80, v112
	v_fmac_f32_e32 v129, v81, v113
	v_fmac_f32_e32 v129, v82, v114
	v_fmac_f32_e32 v129, v83, v115
	v_fmac_f32_e32 v129, v84, v116
	v_fmac_f32_e32 v129, v85, v117
	v_fmac_f32_e32 v129, v86, v118
	v_fmac_f32_e32 v129, v87, v119
	v_fmac_f32_e32 v129, v88, v120
	v_fmac_f32_e32 v129, v89, v121
	v_fmac_f32_e32 v129, v90, v122
	v_fmac_f32_e32 v129, v91, v123
	v_fmac_f32_e32 v129, v92, v124
	v_fmac_f32_e32 v129, v93, v125
	v_fmac_f32_e32 v129, v94, v126
	v_fmac_f32_e32 v129, v95, v127
	v_mul_f32_e32 v132, 0x3fb8aa3b, v128
	v_fma_f32 v133, v128, s50, -v132
	v_rndne_f32_e32 v134, v132
	v_fmac_f32_e32 v133, 0x32a5705f, v128
	v_sub_f32_e32 v132, v132, v134
	v_add_f32_e32 v132, v132, v133
	v_exp_f32_e32 v132, v132
	v_cvt_i32_f32_e32 v133, v134
	v_cmp_ngt_f32_e32 vcc, s51, v128
	v_ldexp_f32 v132, v132, v133
	s_nop 1
	v_cndmask_b32_e32 v132, 0, v132, vcc
	v_cmp_nlt_f32_e32 vcc, s93, v128
	s_nop 1
	v_cndmask_b32_e32 v130, v245, v132, vcc
	v_mul_f32_e32 v132, 0x3fb8aa3b, v129
	v_fma_f32 v133, v129, s50, -v132
	v_rndne_f32_e32 v134, v132
	v_fmac_f32_e32 v133, 0x32a5705f, v129
	v_sub_f32_e32 v132, v132, v134
	v_add_f32_e32 v132, v132, v133
	v_exp_f32_e32 v132, v132
	v_cvt_i32_f32_e32 v133, v134
	v_cmp_ngt_f32_e32 vcc, s51, v129
	v_ldexp_f32 v132, v132, v133
	s_nop 1
	v_cndmask_b32_e32 v132, 0, v132, vcc
	v_cmp_nlt_f32_e32 vcc, s93, v129
	s_nop 1
	v_cndmask_b32_e32 v131, v245, v132, vcc
	v_sub_f32_e32 v130, v130, v131
	v_add_f32_e32 v167, v221, v130
	s_mov_b32 s93, 0
	v_readlane_b32 s8, v254, 44
	v_readlane_b32 s37, v252, 28
	v_readlane_b32 s38, v252, 29
	v_readlane_b32 s39, v252, 30
	v_readlane_b32 s78, v252, 45
	v_readlane_b32 s79, v252, 46
	v_readlane_b32 s80, v252, 47
	v_readlane_b32 s81, v252, 48
	v_readlane_b32 s82, v252, 49
	v_readlane_b32 s83, v252, 50
	v_readlane_b32 s84, v252, 51
	v_readlane_b32 s85, v252, 52
	v_readlane_b32 s86, v252, 53
	v_readlane_b32 s87, v252, 54
	v_readlane_b32 s88, v252, 55
	v_readlane_b32 s89, v252, 56
	v_readlane_b32 s90, v252, 57
	v_readlane_b32 s91, v252, 58
	s_branch .LBB0_429

; #define LAS __attribute__((address_space(3)))
; __device__ __forceinline__ int opaque_tid() { int t = threadIdx.x; asm volatile("" : "+v"(t)); return t; }
; __device__ __forceinline__ int v_st_nat(int k, int c) { return ((k >> 3) * 2 + (c >> 5)) * 512 + ((k & 7) * 32 + (c & 31)) * 2; }
; __device__ __forceinline__ int v_rd_base(int lane) { return ((lane & 3) << 3) | (((lane >> 2) & 3) << 6) | (((lane >> 4) & 1) << 5) | (((lane >> 5) & 1) << 8); }
; #define AT_LOAD(K0, K1, V0, V1, T) do { const size_t e_ = (size_t)(128 * (T) + sr) * 64 + sc; \
;         K0 = *(const bf16x8*)(kcp + e_); V0 = *(const bf16x8*)(vcp + e_); K1 = *(const bf16x8*)(kcp + e_ + 64 * 64); V1 = *(const bf16x8*)(vcp + e_ + 64 * 64); } while (0)
; template <int VAR>
; __device__ __forceinline__ void attn_unit(const Args& a, int l, int b, int h, int qrow0  , bool ctxu, const bf16* Z, bf16* Y, LAS unsigned char* lds) {
;     const int tid = opaque_tid(), lane = tid & 63, wave = __builtin_amdgcn_readfirstlane(tid >> 6), r32 = lane & 31, hi = lane >> 5;
;     const int comp = wave >> 2, wq = wave & 3;
;     const int NT = ctxu ? 2 : 66;
;     const bf16* kcp = (const bf16*)(a.ws + WS_KC) + (size_t)(b * 4 + h) * 8448 * 64; const bf16* vcp = (const bf16*)(a.ws + WS_VC) + (size_t)(b * 4 + h) * 8448 * 64;
;     bf16x8 q0, q1;
;     { const bf16* qp = Z + (size_t)(qrow0 + wq * 32 + r32) * DIN + 512 + h * 64 + comp * 32 + hi * 8; q0 = *(const bf16x8*)(qp); q1 = *(const bf16x8*)(qp + 16); }
;     const int sr = tid >> 3, sc = (tid & 7) * 8;
;     const int kst0 = sr * 144 + sc * 2, kst1 = kst0 + 64 * 144, vst0 = v_st_nat(sr, sc), vst1 = v_st_nat(sr + 64, sc);
;     const int vb0 = (int)(unsigned)(uintptr_t)(lds + AT_V) + v_rd_base(lane);
;     LAS float* wsf = (LAS float*)(lds + AT_WS) + wave * 64;
;     f32x16 negm = f32x16{}, o0 = f32x16{}, o1 = f32x16{}, lacc = f32x16{};
;     float m = 0.f;
;     bf16x8 ka0, ka1, va0, va1, kb0, kb1, vb0_, vb1_;
;     ...
;     AT_LOAD(ka0, ka1, va0, va1, 0); AT_LOAD(kb0, kb1, vb0_, vb1_, 1); AT_STORE(ka0, ka1, va0, va1, 0);
;     const LAS unsigned char* Kb0 = lds + AT_K + comp * 64;
;     for (int t = 0; t < NT; t += 2) {
;         __syncthreads();
;         if (t + 2 < NT) AT_LOAD(ka0, ka1, va0, va1, t + 2);
;         attn_tile(Kb0, vb0, q0, q1, negm, m, o0, o1, lacc, t == 0, wsf, r32, hi);
.LBB0_431:
	v_mov_b32_e32 v79, 0
	v_readfirstlane_b32 s36, v230
	v_readfirstlane_b32 s37, v231
	s_mov_b32 s94, 1
	s_mov_b32 s95, 1
	s_cmp_eq_u32 s93, 3
	s_cselect_b32 s33, 1, 0
	s_lshr_b32 s50, s29, 6
	s_lshl_b32 s51, s50, 10
	s_lshl_b32 s93, s50, 8
	s_lshl_b32 s50, s50, 3
	v_lshrrev_b32_e32 v132, 3, v227
	v_add_u32_e32 v132, s50, v132
	v_bfe_u32 v133, v132, 1, 3
	v_and_b32_e32 v134, 7, v227
	v_xor_b32_e32 v134, v134, v133
	v_lshlrev_b32_e32 v132, 7, v132
	v_lshl_or_b32 v158, v134, 4, v132
	v_add_u32_e32 v159, 0x2000, v158
	v_bfe_u32 v132, v227, 2, 3
	v_add_u32_e32 v132, s50, v132
	v_lshrrev_b32_e32 v133, 5, v227
	v_and_b32_e32 v134, 3, v227
	v_lshlrev_b32_e32 v133, 6, v133
	v_lshl_or_b32 v133, v134, 4, v133
	v_lshl_or_b32 v160, v132, 7, v133
	v_add_u32_e32 v161, 0x2000, v160
	s_lshl_b32 s50, s8, 2
	v_add_u32_e32 v132, s50, v248
	v_bfe_u32 v133, v247, 1, 3
	v_xor_b32_e32 v132, v132, v133
	v_lshlrev_b32_e32 v133, 7, v247
	v_lshl_or_b32 v144, v132, 4, v133
	v_xor_b32_e32 v145, 32, v144
	v_add_u32_e32 v146, 0x3000, v249
	s_add_u32 s93, s93, 0x19800
	v_lshlrev_b32_e32 v132, 2, v247
	v_add_u32_e32 v148, s93, v132
	v_lshlrev_b32_e32 v132, 4, v248
	v_add_u32_e32 v147, s93, v132
	v_mov_b32_e32 v132, 0x19880
	v_mov_b32_e32 v133, 0
	ds_write_b32 v132, v133
	v_mov_b32_e32 v80, 0
	v_mov_b32_e32 v200, 0
	v_mov_b32_e32 v81, 0
	v_mov_b32_e32 v201, 0
	v_mov_b32_e32 v82, 0
	v_mov_b32_e32 v202, 0
	v_mov_b32_e32 v83, 0
	v_mov_b32_e32 v203, 0
	v_mov_b32_e32 v84, 0
	v_mov_b32_e32 v204, 0
	v_mov_b32_e32 v85, 0
	v_mov_b32_e32 v205, 0
	v_mov_b32_e32 v86, 0
	v_mov_b32_e32 v206, 0
	v_mov_b32_e32 v87, 0
	v_mov_b32_e32 v207, 0
	v_mov_b32_e32 v88, 0
	v_mov_b32_e32 v208, 0
	v_mov_b32_e32 v89, 0
	v_mov_b32_e32 v209, 0
	v_mov_b32_e32 v90, 0
	v_mov_b32_e32 v210, 0
	v_mov_b32_e32 v91, 0
	v_mov_b32_e32 v211, 0
	v_mov_b32_e32 v92, 0
	v_mov_b32_e32 v212, 0
	v_mov_b32_e32 v93, 0
	v_mov_b32_e32 v213, 0
	v_mov_b32_e32 v94, 0
	v_mov_b32_e32 v214, 0
	v_mov_b32_e32 v95, 0
	v_mov_b32_e32 v215, 0
	v_mov_b32_e32 v128, 0
	v_mov_b32_e32 v129, 0
	v_mov_b32_e32 v130, 0
	v_mov_b32_e32 v131, 0
	v_mov_b32_e32 v149, 0
	s_sub_u32 s36, s36, s51
	s_subb_u32 s37, s37, 0
	s_add_u32 s48, s36, 0x1d200000
	s_addc_u32 s49, s37, 0
	s_add_u32 s36, s36, 0x1c000000
	s_addc_u32 s37, s37, 0
	s_cmp_eq_u32 s8, 0
	s_cbranch_scc0 .Lat_noprioF
	s_setprio 1
.Lat_noprioF:
	s_waitcnt lgkmcnt(0)
	s_cmp_eq_u32 s33, 1
	s_cbranch_scc1 .Lat_pfskip
	s_add_u32 m0, s51, 0x0
	s_nop 0
	global_load_lds_dwordx4 v158, s[36:37]
	s_add_u32 m0, s51, 0x2000
	s_nop 0
	global_load_lds_dwordx4 v159, s[36:37]
	s_add_u32 m0, s51, 0xc000
	s_nop 0
	global_load_lds_dwordx4 v160, s[48:49]
	s_add_u32 m0, s51, 0xe000
	s_nop 0
	global_load_lds_dwordx4 v161, s[48:49]
.Lat_pfskip:
	s_add_u32 s36, s36, 0x4000
	s_addc_u32 s37, s37, 0
	s_add_u32 s48, s48, 0x4000
	s_addc_u32 s49, s49, 0
	s_mov_b32 s33, 0
	s_add_u32 m0, s51, 0x4000
	s_nop 0
	global_load_lds_dwordx4 v158, s[36:37]
	s_add_u32 m0, s51, 0x6000
	s_nop 0
	global_load_lds_dwordx4 v159, s[36:37]
	s_add_u32 m0, s51, 0x10000
	s_nop 0
	global_load_lds_dwordx4 v160, s[48:49]
	s_add_u32 m0, s51, 0x12000
	s_nop 0
	global_load_lds_dwordx4 v161, s[48:49]
	s_add_u32 s36, s36, 0x4000
	s_addc_u32 s37, s37, 0
	s_add_u32 s48, s48, 0x4000
	s_addc_u32 s49, s49, 0
	s_waitcnt vmcnt(4)
	s_barrier
	s_add_u32 m0, s51, 0x8000
	s_nop 0
	global_load_lds_dwordx4 v158, s[36:37]
	s_add_u32 m0, s51, 0xa000
	s_nop 0
	global_load_lds_dwordx4 v159, s[36:37]
	s_add_u32 m0, s51, 0x14000
	s_nop 0
	global_load_lds_dwordx4 v160, s[48:49]
	s_add_u32 m0, s51, 0x16000
	s_nop 0
	global_load_lds_dwordx4 v161, s[48:49]
	s_add_u32 s36, s36, 0x4000
	s_addc_u32 s37, s37, 0
	s_add_u32 s48, s48, 0x4000
	s_addc_u32 s49, s49, 0
	ds_read_b128 v[48:51], v144 offset:0
	ds_read_b128 v[52:55], v145 offset:0
	ds_read_b128 v[56:59], v144 offset:4096
	ds_read_b128 v[60:63], v145 offset:4096

; #define LAS __attribute__((address_space(3)))
; __device__ __forceinline__ int crow(int r, int hi) { return (r & 3) + 8 * (r >> 2) + 4 * hi; }
; #define AT_LOAD(K0, K1, V0, V1, T) do { const size_t e_ = (size_t)(128 * (T) + sr) * 64 + sc; \
;         K0 = *(const bf16x8*)(kcp + e_); V0 = *(const bf16x8*)(vcp + e_); K1 = *(const bf16x8*)(kcp + e_ + 64 * 64); V1 = *(const bf16x8*)(vcp + e_ + 64 * 64); } while (0)
; template <int VAR>
; __device__ __forceinline__ void attn_unit(const Args& a, int l, int b, int h, int qrow0  , bool ctxu, const bf16* Z, bf16* Y, LAS unsigned char* lds) {
;     ...
;     for (int t = 0; t < NT; t += 2) {
;         __syncthreads();
;         if (t + 2 < NT) AT_LOAD(ka0, ka1, va0, va1, t + 2);
;         attn_tile(Kb0, vb0, q0, q1, negm, m, o0, o1, lacc, t == 0, wsf, r32, hi);
;         AT_STORE(kb0, kb1, vb0_, vb1_, 1);
;         __syncthreads();
;         if (t + 3 < NT) AT_LOAD(kb0, kb1, vb0_, vb1_, t + 3);
;         attn_tile(Kb0 + AT_KB, vb0 + AT_VB, q0, q1, negm, m, o0, o1, lacc, false, wsf, r32, hi);
;         if (t + 2 < NT) AT_STORE(ka0, ka1, va0, va1, 0);
;     }
;     ...
;     float lam, omli;
;     { float s1 = 0.f, s2 = 0.f;
;       for (int i = 0; i < 32; ++i) { s1 += a.lam_q1[l * 32 + i] * a.lam_k1[l * 32 + i]; s2 += a.lam_q2[l * 32 + i] * a.lam_k2[l * 32 + i]; }
;       const float li = 0.8f - 0.6f * expf(-0.3f * (float)l); lam = expf(s1) - expf(s2) + li; omli = 1.f - li; }
;     LAS float* stg = (LAS float*)(lds + AT_ST) + wq * 2048;
;     if (comp == 1) {
; #pragma unroll
;         for (int r = 0; r < 16; ++r) { const int qr = crow(r, hi); const float il = lam * __builtin_amdgcn_rcpf(lacc[r]); stg[qr * 64 + r32] = o0[r] * il; stg[qr * 64 + 32 + r32] = o1[r] * il; }
;     }
;     __syncthreads();
;     if (comp == 0) {
; #pragma unroll
;         for (int r = 0; r < 16; ++r) { const int qr = crow(r, hi); const float il = __builtin_amdgcn_rcpf(lacc[r]); o0[r] = o0[r] * il - stg[qr * 64 + r32]; o1[r] = o1[r] * il - stg[qr * 64 + 32 + r32]; }
;         asm volatile("s_waitcnt lgkmcnt(0)" ::: "memory");
; #pragma unroll
;         for (int r = 0; r < 16; ++r) { const int qr = crow(r, hi); stg[qr * 64 + r32] = o0[r]; stg[qr * 64 + 32 + r32] = o1[r]; }
.Lat_ndF5:
	ds_read_b128 v[48:51], v144 offset:0
	ds_read_b128 v[52:55], v145 offset:0
	ds_read_b128 v[56:59], v144 offset:4096
	ds_read_b128 v[60:63], v145 offset:4096
	v_mfma_f32_32x32x16_bf16 v[80:95], v[162:165], v[192:195], v[80:95]
	v_mfma_f32_32x32x16_bf16 v[200:215], v[162:165], v[196:199], v[200:215]
	s_add_u32 s33, s33, 1
	s_cmp_lt_u32 s33, 22
	s_cbranch_scc1 .Lat_floop
	v_add_f32_e32 v132, v128, v129
	v_mov_b32_e32 v133, v132
	s_nop 1
	v_permlane32_swap_b32_e32 v132, v133
	v_add_f32_e32 v135, v132, v133
	v_add_f32_e32 v132, v130, v131
	v_mov_b32_e32 v133, v132
	s_nop 1
	v_permlane32_swap_b32_e32 v132, v133
	v_add_f32_e32 v130, v132, v133
	s_nop 7
	s_nop 7
	v_add_f32_e32 v132, v135, v130
	v_mov_b32_e32 v133, 0
	v_add_f32_e64 v132, v132, |v0|
	v_add_f32_e64 v133, v133, |v1|
	v_add_f32_e64 v132, v132, |v2|
	v_add_f32_e64 v133, v133, |v3|
	v_add_f32_e64 v132, v132, |v4|
	v_add_f32_e64 v133, v133, |v5|
	v_add_f32_e64 v132, v132, |v6|
	v_add_f32_e64 v133, v133, |v7|
	v_add_f32_e64 v132, v132, |v8|
	v_add_f32_e64 v133, v133, |v9|
	v_add_f32_e64 v132, v132, |v10|
	v_add_f32_e64 v133, v133, |v11|
	v_add_f32_e64 v132, v132, |v12|
	v_add_f32_e64 v133, v133, |v13|
	v_add_f32_e64 v132, v132, |v14|
	v_add_f32_e64 v133, v133, |v15|
	v_add_f32_e64 v132, v132, |v16|
	v_add_f32_e64 v133, v133, |v17|
	v_add_f32_e64 v132, v132, |v18|
	v_add_f32_e64 v133, v133, |v19|
	v_add_f32_e64 v132, v132, |v20|
	v_add_f32_e64 v133, v133, |v21|
	v_add_f32_e64 v132, v132, |v22|
	v_add_f32_e64 v133, v133, |v23|
	v_add_f32_e64 v132, v132, |v24|
	v_add_f32_e64 v133, v133, |v25|
	v_add_f32_e64 v132, v132, |v26|
	v_add_f32_e64 v133, v133, |v27|
	v_add_f32_e64 v132, v132, |v28|
	v_add_f32_e64 v133, v133, |v29|
	v_add_f32_e64 v132, v132, |v30|
	v_add_f32_e64 v133, v133, |v31|
	v_add_f32_e64 v132, v132, |v80|
	v_add_f32_e64 v133, v133, |v81|
	v_add_f32_e64 v132, v132, |v82|
	v_add_f32_e64 v133, v133, |v83|
	v_add_f32_e64 v132, v132, |v84|
	v_add_f32_e64 v133, v133, |v85|
	v_add_f32_e64 v132, v132, |v86|
	v_add_f32_e64 v133, v133, |v87|
	v_add_f32_e64 v132, v132, |v88|
	v_add_f32_e64 v133, v133, |v89|
	v_add_f32_e64 v132, v132, |v90|
	v_add_f32_e64 v133, v133, |v91|
	v_add_f32_e64 v132, v132, |v92|
	v_add_f32_e64 v133, v133, |v93|
	v_add_f32_e64 v132, v132, |v94|
	v_add_f32_e64 v133, v133, |v95|
	v_add_f32_e64 v132, v132, |v200|
	v_add_f32_e64 v133, v133, |v201|
	v_add_f32_e64 v132, v132, |v202|
	v_add_f32_e64 v133, v133, |v203|
	v_add_f32_e64 v132, v132, |v204|
	v_add_f32_e64 v133, v133, |v205|
	v_add_f32_e64 v132, v132, |v206|
	v_add_f32_e64 v133, v133, |v207|
	v_add_f32_e64 v132, v132, |v208|
	v_add_f32_e64 v133, v133, |v209|
	v_add_f32_e64 v132, v132, |v210|
	v_add_f32_e64 v133, v133, |v211|
	v_add_f32_e64 v132, v132, |v212|
	v_add_f32_e64 v133, v133, |v213|
	v_add_f32_e64 v132, v132, |v214|
	v_add_f32_e64 v133, v133, |v215|
	v_add_f32_e32 v132, v132, v133
	v_mov_b32_e32 v133, 0x76800000
	v_cmp_nlt_f32_e32 vcc, v132, v133
	s_cmp_lg_u64 vcc, 0
	s_cselect_b32 s50, 1, 0
	v_mov_b32_e32 v134, 0x19880
	v_mov_b32_e32 v133, s50
	ds_or_b32 v134, v133
	s_nop 7
	s_waitcnt lgkmcnt(0)
	ds_write_b32 v148, v135
	s_waitcnt lgkmcnt(0)
	ds_read_b128 v[32:35], v147 offset:0
	ds_read_b128 v[36:39], v147 offset:32
	ds_read_b128 v[40:43], v147 offset:64
	ds_read_b128 v[44:47], v147 offset:96
	s_waitcnt lgkmcnt(0)
	ds_write_b32 v148, v130
	s_waitcnt lgkmcnt(0)
	ds_read_b128 v[104:107], v147 offset:0
	ds_read_b128 v[108:111], v147 offset:32
	ds_read_b128 v[112:115], v147 offset:64
	ds_read_b128 v[116:119], v147 offset:96
	s_waitcnt lgkmcnt(0)
	s_waitcnt vmcnt(0)
	v_or_b32_e32 v132, s58, v228
	v_mov_b32_e32 v133, 0
	v_lshl_add_u64 v[132:133], v[132:133], 2, s[78:79]
	global_load_dwordx4 v[100:103], v[132:133], off offset:16
	global_load_dwordx4 v[96:99], v[132:133], off
	s_setprio 0
	s_bfe_u32 s9, s29, 0x20006
	s_lshl_b32 s9, s9, 13
	s_add_i32 s9, s9, 0x4000
	v_lshlrev_b32_e32 v162, 10, v248
	v_lshlrev_b32_e32 v163, 2, v247
	v_add3_u32 v52, s9, v162, v163
	s_add_i32 s50, s9, 0xd800
	v_add_u32_e32 v164, 0xd800, v52
	s_ashr_i32 s8, s29, 8
	s_cmp_eq_u32 s8, 1
	s_cbranch_scc1 .Lat_e1c1
	v_rcp_f32_e32 v68, v32
	v_rcp_f32_e32 v67, v33
	v_rcp_f32_e32 v66, v34
	v_rcp_f32_e32 v65, v35
	v_rcp_f32_e32 v64, v36
	v_rcp_f32_e32 v63, v37
	v_rcp_f32_e32 v62, v38
	v_rcp_f32_e32 v61, v39
	v_rcp_f32_e32 v60, v40
	v_rcp_f32_e32 v59, v41
	v_rcp_f32_e32 v58, v42
	v_rcp_f32_e32 v57, v43
	v_rcp_f32_e32 v56, v44
	v_rcp_f32_e32 v55, v45
	v_rcp_f32_e32 v54, v46
	v_rcp_f32_e32 v53, v47
	v_rcp_f32_e32 v120, v104
	v_rcp_f32_e32 v121, v105
	v_rcp_f32_e32 v122, v106
	v_rcp_f32_e32 v123, v107
	v_rcp_f32_e32 v124, v108
	v_rcp_f32_e32 v125, v109
	v_rcp_f32_e32 v126, v110
	v_rcp_f32_e32 v127, v111
	v_rcp_f32_e32 v128, v112
	v_rcp_f32_e32 v129, v113
	v_rcp_f32_e32 v130, v114
	v_rcp_f32_e32 v131, v115
	v_rcp_f32_e32 v132, v116
	v_rcp_f32_e32 v133, v117
	v_rcp_f32_e32 v134, v118
	v_rcp_f32_e32 v135, v119
	v_mov_b32_e32 v165, v52
	v_mul_f32_e32 v162, v80, v120
	v_mul_f32_e32 v163, v200, v120
	ds_write2_b32 v165, v162, v163 offset1:32
	v_mul_f32_e32 v162, v81, v121
	v_mul_f32_e32 v163, v201, v121
	ds_write2_b32 v165, v162, v163 offset0:64 offset1:96
	v_mul_f32_e32 v162, v82, v122
	v_mul_f32_e32 v163, v202, v122
	ds_write2_b32 v165, v162, v163 offset0:128 offset1:160
	v_mul_f32_e32 v162, v83, v123
	v_mul_f32_e32 v163, v203, v123
	ds_write2_b32 v165, v162, v163 offset0:192 offset1:224
	v_add_u32_e32 v165, 0x800, v52
	v_mul_f32_e32 v162, v84, v124
	v_mul_f32_e32 v163, v204, v124
	ds_write2_b32 v165, v162, v163 offset1:32
	v_mul_f32_e32 v162, v85, v125
	v_mul_f32_e32 v163, v205, v125
	ds_write2_b32 v165, v162, v163 offset0:64 offset1:96
	v_mul_f32_e32 v162, v86, v126
	v_mul_f32_e32 v163, v206, v126
	ds_write2_b32 v165, v162, v163 offset0:128 offset1:160
	v_mul_f32_e32 v162, v87, v127
	v_mul_f32_e32 v163, v207, v127
	ds_write2_b32 v165, v162, v163 offset0:192 offset1:224
	v_add_u32_e32 v165, 0x1000, v52
	v_mul_f32_e32 v162, v88, v128
	v_mul_f32_e32 v163, v208, v128
	ds_write2_b32 v165, v162, v163 offset1:32
	v_mul_f32_e32 v162, v89, v129
	v_mul_f32_e32 v163, v209, v129
	ds_write2_b32 v165, v162, v163 offset0:64 offset1:96
	v_mul_f32_e32 v162, v90, v130
	v_mul_f32_e32 v163, v210, v130
	ds_write2_b32 v165, v162, v163 offset0:128 offset1:160
	v_mul_f32_e32 v162, v91, v131
	v_mul_f32_e32 v163, v211, v131
	ds_write2_b32 v165, v162, v163 offset0:192 offset1:224
	v_add_u32_e32 v165, 0x1800, v52
	v_mul_f32_e32 v162, v92, v132
	v_mul_f32_e32 v163, v212, v132
	ds_write2_b32 v165, v162, v163 offset1:32
	v_mul_f32_e32 v162, v93, v133
	v_mul_f32_e32 v163, v213, v133
	ds_write2_b32 v165, v162, v163 offset0:64 offset1:96
	v_mul_f32_e32 v162, v94, v134
	v_mul_f32_e32 v163, v214, v134
	ds_write2_b32 v165, v162, v163 offset0:128 offset1:160
	v_mul_f32_e32 v162, v95, v135
	v_mul_f32_e32 v163, v215, v135
	ds_write2_b32 v165, v162, v163 offset0:192 offset1:224
	v_mov_b32_e32 v52, v164
	s_mov_b32 s9, s50
	s_branch .Lat_e1join

; __device__ __forceinline__ int crow(int r, int hi) { return (r & 3) + 8 * (r >> 2) + 4 * hi; }
; #define AT_LOAD(K0, K1, V0, V1, T) do { const size_t e_ = (size_t)(128 * (T) + sr) * 64 + sc; \
;         K0 = *(const bf16x8*)(kcp + e_); V0 = *(const bf16x8*)(vcp + e_); K1 = *(const bf16x8*)(kcp + e_ + 64 * 64); V1 = *(const bf16x8*)(vcp + e_ + 64 * 64); } while (0)
; #define AT_STORE(K0, K1, V0, V1, BUF) do { *(LAS bf16x8*)(lds + AT_K + (BUF) * AT_KB + kst0) = K0; *(LAS bf16x8*)(lds + AT_K + (BUF) * AT_KB + kst1) = K1; \
;         *(LAS bf16x8*)(lds + AT_V + (BUF) * AT_VB + vst0) = V0; *(LAS bf16x8*)(lds + AT_V + (BUF) * AT_VB + vst1) = V1; } while (0)
; template <int VAR>
; __device__ __forceinline__ void attn_unit(const Args& a, int l, int b, int h, int qrow0  , bool ctxu, const bf16* Z, bf16* Y, LAS unsigned char* lds) {
;     ...
;     AT_LOAD(ka0, ka1, va0, va1, 0); AT_LOAD(kb0, kb1, vb0_, vb1_, 1); AT_STORE(ka0, ka1, va0, va1, 0);
;     ...
;     if (comp == 1) {
; #pragma unroll
;         for (int r = 0; r < 16; ++r) { const int qr = crow(r, hi); const float il = lam * __builtin_amdgcn_rcpf(lacc[r]); stg[qr * 64 + r32] = o0[r] * il; stg[qr * 64 + 32 + r32] = o1[r] * il; }
;     }
;     __syncthreads();
;     if (comp == 0) {
.Lat_e1join:
	s_waitcnt lgkmcnt(0)
	s_barrier
	v_mov_b32_e32 v162, 0x19880
	ds_read_b32 v162, v162
	s_waitcnt lgkmcnt(0)
	v_readfirstlane_b32 s50, v162
	s_cmp_lg_u32 s50, 0
	s_cbranch_scc1 .Lat_safe_entry
	s_cmp_eq_u32 s8, 1
	s_cbranch_scc0 .Lat_e1r0
	s_or_b32 s60, s60, 0x1000
	v_xor_b32_e32 v226, 0x80000000, v226
.Lat_e1r0:
	s_mov_b32 s93, 2
	s_waitcnt vmcnt(0)
	s_cmp_eq_u32 s59, 0
	s_cbranch_scc0 .Lat_nopf
	s_add_u32 m0, s51, 0x0
	s_nop 0
	global_load_lds_dwordx4 v158, s[36:37]
	s_add_u32 m0, s51, 0x2000
	s_nop 0
	global_load_lds_dwordx4 v159, s[36:37]
	s_add_u32 m0, s51, 0xc000
	s_nop 0
	global_load_lds_dwordx4 v160, s[48:49]
	s_add_u32 m0, s51, 0xe000
	s_nop 0
	global_load_lds_dwordx4 v161, s[48:49]
	s_mov_b32 s93, 3

; __global__ void __launch_bounds__(512, 2) fwd_megakernel(Args a) {
;     ...
;                 for (int i = 0;; ++i) { const int j = xm ? cu + i * per : blk + i * G; if (j >= (xm ? 128 : 1024)) break;
;                     const int bh = xm ? xcd * 2 + (j >> 6) : (j >> 6), qb = j & 63; if (rep_ == 0) attn_unit<0>(a, l, bh >> 2, bh & 3, (bh >> 2) * SEQ + qb * 128, false, Zb, Yb, lds); else attn_unit<PROBE_VAR>(a, l, bh >> 2, bh & 3, (bh >> 2) * SEQ + qb * 128, false, Zb, (bf16*)(ws + 384 * MiB), lds); }
.Lat_afterA:
	s_cmp_ge_u32 s93, 2
	s_cbranch_scc0 .Lat_after2p
	s_ashr_i32 s8, s29, 8
	s_cmp_eq_u32 s8, 1
	s_cbranch_scc0 .Lat_done1
	v_xor_b32_e32 v226, 0x80000000, v226

; __device__ __forceinline__ int crow(int r, int hi) { return (r & 3) + 8 * (r >> 2) + 4 * hi; }
; #define AT_LOAD(K0, K1, V0, V1, T) do { const size_t e_ = (size_t)(128 * (T) + sr) * 64 + sc; \
;         K0 = *(const bf16x8*)(kcp + e_); V0 = *(const bf16x8*)(vcp + e_); K1 = *(const bf16x8*)(kcp + e_ + 64 * 64); V1 = *(const bf16x8*)(vcp + e_ + 64 * 64); } while (0)
; #define AT_STORE(K0, K1, V0, V1, BUF) do { *(LAS bf16x8*)(lds + AT_K + (BUF) * AT_KB + kst0) = K0; *(LAS bf16x8*)(lds + AT_K + (BUF) * AT_KB + kst1) = K1; \
;         *(LAS bf16x8*)(lds + AT_V + (BUF) * AT_VB + vst0) = V0; *(LAS bf16x8*)(lds + AT_V + (BUF) * AT_VB + vst1) = V1; } while (0)
; template <int VAR>
; __device__ __forceinline__ void attn_unit(const Args& a, int l, int b, int h, int qrow0  , bool ctxu, const bf16* Z, bf16* Y, LAS unsigned char* lds) {
;     ...
;     for (int t = 0; t < NT; t += 2) {
;         __syncthreads();
;         if (t + 2 < NT) AT_LOAD(ka0, ka1, va0, va1, t + 2);
;         attn_tile(Kb0, vb0, q0, q1, negm, m, o0, o1, lacc, t == 0, wsf, r32, hi);
;         AT_STORE(kb0, kb1, vb0_, vb1_, 1);
;         __syncthreads();
;         if (t + 3 < NT) AT_LOAD(kb0, kb1, vb0_, vb1_, t + 3);
;         attn_tile(Kb0 + AT_KB, vb0 + AT_VB, q0, q1, negm, m, o0, o1, lacc, false, wsf, r32, hi);
;         if (t + 2 < NT) AT_STORE(ka0, ka1, va0, va1, 0);
;     }
;     ...
;     if (comp == 0) {
; #pragma unroll
;         for (int r = 0; r < 16; ++r) { const int qr = crow(r, hi); const float il = __builtin_amdgcn_rcpf(lacc[r]); o0[r] = o0[r] * il - stg[qr * 64 + r32]; o1[r] = o1[r] * il - stg[qr * 64 + 32 + r32]; }
;         asm volatile("s_waitcnt lgkmcnt(0)" ::: "memory");
; #pragma unroll
;         for (int r = 0; r < 16; ++r) { const int qr = crow(r, hi); stg[qr * 64 + r32] = o0[r]; stg[qr * 64 + 32 + r32] = o1[r]; }
;         asm volatile("s_waitcnt lgkmcnt(0)" ::: "memory");
;         const int ch = lane & 7;
;         float gsub[8];
; #pragma unroll
;         for (int i = 0; i < 8; ++i) gsub[i] = a.subln_g[l * 64 + ch * 8 + i] * omli;
.Lat_ndg5:
	ds_read_b128 v[48:51], v144 offset:0
	ds_read_b128 v[52:55], v145 offset:0
	ds_read_b128 v[56:59], v144 offset:4096
	ds_read_b128 v[60:63], v145 offset:4096
	v_mfma_f32_32x32x16_bf16 v[80:95], v[162:165], v[192:195], v[80:95]
	v_mfma_f32_32x32x16_bf16 v[200:215], v[162:165], v[196:199], v[200:215]
	s_add_u32 s33, s33, 1
	s_cmp_lt_u32 s33, 22
	s_cbranch_scc1 .Lat_loop
	v_add_f32_e32 v132, v128, v129
	v_mov_b32_e32 v133, v132
	s_nop 1
	v_permlane32_swap_b32_e32 v132, v133
	v_add_f32_e32 v135, v132, v133
	v_add_f32_e32 v132, v130, v131
	v_mov_b32_e32 v133, v132
	s_nop 1
	v_permlane32_swap_b32_e32 v132, v133
	v_add_f32_e32 v130, v132, v133
	s_nop 7
	s_waitcnt lgkmcnt(0)
	ds_write_b32 v148, v135
	s_waitcnt lgkmcnt(0)
	ds_read_b128 v[32:35], v147 offset:0
	ds_read_b128 v[36:39], v147 offset:32
	ds_read_b128 v[40:43], v147 offset:64
	ds_read_b128 v[44:47], v147 offset:96
	s_waitcnt lgkmcnt(0)
	s_bfe_u32 s9, s29, 0x20006
	s_ashr_i32 s8, s29, 8
	s_mov_b32 s93, 0
	s_waitcnt vmcnt(0)
	v_or_b32_e32 v132, s58, v228
	v_mov_b32_e32 v133, 0
	v_lshl_add_u64 v[132:133], v[132:133], 2, s[78:79]
	global_load_dwordx4 v[100:103], v[132:133], off offset:16
	global_load_dwordx4 v[96:99], v[132:133], off
	s_waitcnt vmcnt(0)
	s_setprio 0
	s_branch .LBB0_459

; #define LAS __attribute__((address_space(3)))
; __device__ __forceinline__ float sum8(float v) { v += dppmov<0xB1>(v); v += dppmov<0x4E>(v); v += dppmov<0x141>(v); return v; }
; __device__ __forceinline__ u32x4 pk8(const float (&v)[8]) { u32x4 w; w.x = pk2(v[0], v[1]); w.y = pk2(v[2], v[3]); w.z = pk2(v[4], v[5]); w.w = pk2(v[6], v[7]); return w; }
; __device__ __forceinline__ int crow(int r, int hi) { return (r & 3) + 8 * (r >> 2) + 4 * hi; }
; template <int VAR>
; __device__ __forceinline__ void attn_unit(const Args& a, int l, int b, int h, int qrow0  , bool ctxu, const bf16* Z, bf16* Y, LAS unsigned char* lds) {
;     ...
;     if (comp == 0) {
; #pragma unroll
;         for (int r = 0; r < 16; ++r) { const int qr = crow(r, hi); const float il = __builtin_amdgcn_rcpf(lacc[r]); o0[r] = o0[r] * il - stg[qr * 64 + r32]; o1[r] = o1[r] * il - stg[qr * 64 + 32 + r32]; }
;         asm volatile("s_waitcnt lgkmcnt(0)" ::: "memory");
; #pragma unroll
;         for (int r = 0; r < 16; ++r) { const int qr = crow(r, hi); stg[qr * 64 + r32] = o0[r]; stg[qr * 64 + 32 + r32] = o1[r]; }
;         asm volatile("s_waitcnt lgkmcnt(0)" ::: "memory");
;         const int ch = lane & 7;
;         float gsub[8];
; #pragma unroll
;         for (int i = 0; i < 8; ++i) gsub[i] = a.subln_g[l * 64 + ch * 8 + i] * omli;
; #pragma unroll
;         for (int i = 0; i < 4; ++i) { const int row = i * 8 + (lane >> 3);
;             const f32x4 x0 = *(const LAS f32x4*)(stg + row * 64 + ch * 8), x1 = *(const LAS f32x4*)(stg + row * 64 + ch * 8 + 4);
;             float ss = (x0.x * x0.x + x0.y * x0.y) + (x0.z * x0.z + x0.w * x0.w) + (x1.x * x1.x + x1.y * x1.y) + (x1.z * x1.z + x1.w * x1.w);
;             ss = sum8(ss);
;             const float rs = rsqrtf(ss * (1.f / 64.f) + 1e-6f);
;             float o[8] = {x0.x * rs * gsub[0], x0.y * rs * gsub[1], x0.z * rs * gsub[2], x0.w * rs * gsub[3], x1.x * rs * gsub[4], x1.y * rs * gsub[5], x1.z * rs * gsub[6], x1.w * rs * gsub[7]};
;             *(u32x4*)(Y + (size_t)(qrow0 + wq * 32 + row) * DM + 256 + h * 64 + ch * 8) = pk8(o); }
.Lat_ep462:
	v_add_u32_e32 v33, 0x800, v52
	v_add_u32_e32 v35, 0x1000, v52
	v_add_u32_e32 v36, 0x1800, v52
	ds_read2_b32 v[168:169], v52 offset1:32
	ds_read2_b32 v[170:171], v52 offset0:64 offset1:96
	ds_read2_b32 v[172:173], v52 offset0:128 offset1:160
	ds_read2_b32 v[174:175], v52 offset0:192 offset1:224
	ds_read2_b32 v[176:177], v33 offset1:32
	ds_read2_b32 v[178:179], v33 offset0:64 offset1:96
	ds_read2_b32 v[180:181], v33 offset0:128 offset1:160
	ds_read2_b32 v[182:183], v33 offset0:192 offset1:224
	ds_read2_b32 v[184:185], v35 offset1:32
	ds_read2_b32 v[186:187], v35 offset0:64 offset1:96
	ds_read2_b32 v[188:189], v35 offset0:128 offset1:160
	ds_read2_b32 v[190:191], v35 offset0:192 offset1:224
	v_readlane_b32 s76, v252, 43
	v_or_b32_e32 v216, s58, v228
	v_readlane_b32 s78, v252, 45
	v_readlane_b32 s79, v252, 46
	s_lshl_b32 s72, s28, 1
	v_readlane_b32 s77, v252, 44
	v_readlane_b32 s80, v252, 47
	v_readlane_b32 s81, v252, 48
	v_readlane_b32 s82, v252, 49
	v_readlane_b32 s83, v252, 50
	v_readlane_b32 s84, v252, 51
	v_readlane_b32 s85, v252, 52
	v_readlane_b32 s86, v252, 53
	v_readlane_b32 s87, v252, 54
	v_readlane_b32 s88, v252, 55
	v_readlane_b32 s89, v252, 56
	v_readlane_b32 s90, v252, 57
	v_readlane_b32 s91, v252, 58
	s_waitcnt lgkmcnt(8)
	v_fma_f32 v34, v0, v68, -v168
	v_fma_f32 v16, v16, v68, -v169
	v_fma_f32 v32, v1, v67, -v170
	v_fma_f32 v17, v17, v67, -v171
	v_fma_f32 v2, v2, v66, -v172
	v_fma_f32 v18, v18, v66, -v173
	v_fma_f32 v3, v3, v65, -v174
	v_fma_f32 v19, v19, v65, -v175
	ds_read2_b32 v[192:193], v36 offset1:32
	ds_read2_b32 v[194:195], v36 offset0:64 offset1:96
	ds_read2_b32 v[196:197], v36 offset0:128 offset1:160
	ds_read2_b32 v[198:199], v36 offset0:192 offset1:224
	s_waitcnt lgkmcnt(8)
	v_fma_f32 v4, v4, v64, -v176
	v_fma_f32 v20, v20, v64, -v177
	v_fma_f32 v5, v5, v63, -v178
	v_fma_f32 v21, v21, v63, -v179
	v_fma_f32 v6, v6, v62, -v180
	v_fma_f32 v22, v22, v62, -v181
	v_fma_f32 v7, v7, v61, -v182
	v_fma_f32 v23, v23, v61, -v183
	s_waitcnt lgkmcnt(4)
	v_fma_f32 v8, v8, v60, -v184
	v_fma_f32 v24, v24, v60, -v185
	v_fma_f32 v9, v9, v59, -v186
	v_fma_f32 v25, v25, v59, -v187
	v_fma_f32 v10, v10, v58, -v188
	v_fma_f32 v26, v26, v58, -v189
	v_fma_f32 v11, v11, v57, -v190
	v_fma_f32 v27, v27, v57, -v191
	s_waitcnt lgkmcnt(0)
	v_fma_f32 v12, v12, v56, -v192
	v_fma_f32 v28, v28, v56, -v193
	v_fma_f32 v13, v13, v55, -v194
	v_fma_f32 v29, v29, v55, -v195
	v_fma_f32 v14, v14, v54, -v196
	v_fma_f32 v30, v30, v54, -v197
	v_fma_f32 v0, v15, v53, -v198
	v_fma_f32 v1, v31, v53, -v199
	ds_write2_b32 v52, v34, v16 offset1:32
	ds_write2_b32 v52, v32, v17 offset0:64 offset1:96
	ds_write2_b32 v52, v2, v18 offset0:128 offset1:160
	ds_write2_b32 v52, v3, v19 offset0:192 offset1:224
	ds_write2_b32 v33, v4, v20 offset1:32
	ds_write2_b32 v33, v5, v21 offset0:64 offset1:96
	ds_write2_b32 v33, v6, v22 offset0:128 offset1:160
	ds_write2_b32 v33, v7, v23 offset0:192 offset1:224
	ds_write2_b32 v35, v8, v24 offset1:32
	ds_write2_b32 v35, v9, v25 offset0:64 offset1:96
	ds_write2_b32 v35, v10, v26 offset0:128 offset1:160
	ds_write2_b32 v35, v11, v27 offset0:192 offset1:224
	ds_write2_b32 v36, v12, v28 offset1:32
	ds_write2_b32 v36, v13, v29 offset0:64 offset1:96
	ds_write2_b32 v36, v14, v30 offset0:128 offset1:160
	ds_write2_b32 v36, v0, v1 offset0:192 offset1:224
	s_waitcnt lgkmcnt(0)
	v_lshrrev_b32_e32 v32, 3, v227
	v_lshl_add_u32 v33, v228, 2, s9
	v_lshl_add_u32 v0, v32, 8, v33
	ds_read_b128 v[8:11], v0
	ds_read_b128 v[16:19], v0 offset:16
	v_lshlrev_b32_e32 v216, 1, v228
	s_waitcnt lgkmcnt(1)
	v_pk_mul_f32 v[0:1], v[10:11], v[10:11]
	v_pk_mul_f32 v[2:3], v[8:9], v[8:9]
	v_mov_b32_e32 v227, v8
	v_pk_mov_b32 v[20:21], v[2:3], v[0:1] op_sel:[1,0]
	v_mov_b32_e32 v3, v1
	v_pk_add_f32 v[0:1], v[20:21], v[2:3]
	s_waitcnt lgkmcnt(0)
	v_pk_mul_f32 v[2:3], v[18:19], v[18:19]
	v_pk_mul_f32 v[20:21], v[16:17], v[16:17]
	v_mov_b32_e32 v22, v2
	v_mov_b32_e32 v23, v20
	v_mov_b32_e32 v20, v3
	v_pk_add_f32 v[2:3], v[22:23], v[20:21]
	v_add_f32_e32 v0, v0, v1
	v_add_f32_e32 v0, v0, v3
	v_add_f32_e32 v0, v2, v0
	v_mov_b32_e32 v20, v96
	v_add_f32_dpp v0, v0, v0 quad_perm:[1,0,3,2] row_mask:0xf bank_mask:0xf bound_ctrl:1
	s_nop 1
	v_add_f32_dpp v0, v0, v0 quad_perm:[2,3,0,1] row_mask:0xf bank_mask:0xf bound_ctrl:1
	s_nop 1
	v_add_f32_dpp v0, v0, v0 row_half_mirror row_mask:0xf bank_mask:0xf bound_ctrl:1
	v_fmamk_f32 v0, v0, 0x3c800000, v218
	v_cmp_gt_f32_e32 vcc, s66, v0
	v_mul_f32_e32 v1, 0x4b800000, v0
	s_nop 0
	v_cndmask_b32_e32 v0, v0, v1, vcc
	v_rsq_f32_e32 v0, v0
	s_nop 0
	v_mul_f32_e32 v1, 0x45800000, v0
	v_cndmask_b32_e32 v21, v0, v1, vcc
	v_pk_mul_f32 v[0:1], v[226:227], v[20:21]
	v_mov_b32_e32 v227, v9
	v_mov_b32_e32 v20, v97
	v_pk_mul_f32 v[2:3], v[226:227], v[20:21]
	v_mov_b32_e32 v227, v10
	v_mov_b32_e32 v20, v98
	v_pk_mul_f32 v[4:5], v[226:227], v[20:21]
	v_mov_b32_e32 v227, v11
	v_mov_b32_e32 v20, v99
	v_pk_mul_f32 v[6:7], v[226:227], v[20:21]
	v_mov_b32_e32 v227, v16
	v_mov_b32_e32 v20, v100
	v_pk_mul_f32 v[8:9], v[226:227], v[20:21]
	v_mov_b32_e32 v227, v17
	v_mov_b32_e32 v20, v101
	v_pk_mul_f32 v[10:11], v[226:227], v[20:21]
	v_mov_b32_e32 v227, v18
	v_mov_b32_e32 v20, v102
	v_pk_mul_f32 v[12:13], v[226:227], v[20:21]
	v_mov_b32_e32 v227, v19
	v_mov_b32_e32 v20, v103
	v_pk_mul_f32 v[14:15], v[226:227], v[20:21]
	v_or_b32_e32 v20, s60, v32
	v_ashrrev_i32_e32 v21, 31, v20
	v_lshlrev_b64 v[20:21], 11, v[20:21]
	v_lshl_add_u64 v[20:21], s[20:21], 0, v[20:21]
	v_mul_f32_e32 v1, v0, v1
	v_lshl_add_u64 v[20:21], v[20:21], 0, s[72:73]
	v_mul_f32_e32 v3, v2, v3
	v_cvt_pk_bf16_f32 v16, v1, v3
	v_lshl_add_u64 v[20:21], v[20:21], 0, v[216:217]
	v_or_b32_e32 v1, 8, v32
	v_mul_f32_e32 v5, v4, v5
	v_mul_f32_e32 v7, v6, v7
	v_mul_f32_e32 v9, v8, v9
	v_mul_f32_e32 v11, v10, v11
	v_mul_f32_e32 v13, v12, v13
	v_mul_f32_e32 v15, v14, v15
	v_cvt_pk_bf16_f32 v17, v5, v7
	v_cvt_pk_bf16_f32 v18, v9, v11
	v_cvt_pk_bf16_f32 v19, v13, v15
	global_store_dwordx4 v[20:21], v[16:19], off offset:512
	v_lshl_add_u32 v3, v1, 8, v33
	ds_read_b128 v[16:19], v3
	ds_read_b128 v[20:23], v3 offset:16
	s_waitcnt lgkmcnt(1)
; #define LAS __attribute__((address_space(3)))
; __device__ __forceinline__ float sum8(float v) { v += dppmov<0xB1>(v); v += dppmov<0x4E>(v); v += dppmov<0x141>(v); return v; }
; __device__ __forceinline__ u32x4 pk8(const float (&v)[8]) { u32x4 w; w.x = pk2(v[0], v[1]); w.y = pk2(v[2], v[3]); w.z = pk2(v[4], v[5]); w.w = pk2(v[6], v[7]); return w; }
; template <int VAR>
; __device__ __forceinline__ void attn_unit(const Args& a, int l, int b, int h, int qrow0  , bool ctxu, const bf16* Z, bf16* Y, LAS unsigned char* lds) {
;     ...
;         for (int i = 0; i < 4; ++i) { const int row = i * 8 + (lane >> 3);
;             const f32x4 x0 = *(const LAS f32x4*)(stg + row * 64 + ch * 8), x1 = *(const LAS f32x4*)(stg + row * 64 + ch * 8 + 4);
;             float ss = (x0.x * x0.x + x0.y * x0.y) + (x0.z * x0.z + x0.w * x0.w) + (x1.x * x1.x + x1.y * x1.y) + (x1.z * x1.z + x1.w * x1.w);
;             ss = sum8(ss);
;             const float rs = rsqrtf(ss * (1.f / 64.f) + 1e-6f);
;             float o[8] = {x0.x * rs * gsub[0], x0.y * rs * gsub[1], x0.z * rs * gsub[2], x0.w * rs * gsub[3], x1.x * rs * gsub[4], x1.y * rs * gsub[5], x1.z * rs * gsub[6], x1.w * rs * gsub[7]};
;             *(u32x4*)(Y + (size_t)(qrow0 + wq * 32 + row) * DM + 256 + h * 64 + ch * 8) = pk8(o); }
	v_pk_mul_f32 v[24:25], v[18:19], v[18:19]
	v_pk_mul_f32 v[26:27], v[16:17], v[16:17]
	s_nop 0
	v_pk_mov_b32 v[28:29], v[26:27], v[24:25] op_sel:[1,0]
	v_mov_b32_e32 v27, v25
	v_pk_add_f32 v[24:25], v[28:29], v[26:27]
	s_waitcnt lgkmcnt(0)
	v_pk_mul_f32 v[26:27], v[22:23], v[22:23]
	v_pk_mul_f32 v[28:29], v[20:21], v[20:21]
	v_mov_b32_e32 v30, v26
	v_mov_b32_e32 v31, v28
	v_mov_b32_e32 v28, v27
	v_pk_add_f32 v[26:27], v[30:31], v[28:29]
	v_add_f32_e32 v3, v24, v25
	v_add_f32_e32 v3, v3, v27
	v_add_f32_e32 v3, v26, v3
	s_nop 1
	v_add_f32_dpp v3, v3, v3 quad_perm:[1,0,3,2] row_mask:0xf bank_mask:0xf bound_ctrl:1
	s_nop 1
	v_add_f32_dpp v3, v3, v3 quad_perm:[2,3,0,1] row_mask:0xf bank_mask:0xf bound_ctrl:1
	s_nop 1
	v_add_f32_dpp v3, v3, v3 row_half_mirror row_mask:0xf bank_mask:0xf bound_ctrl:1
	v_fmamk_f32 v3, v3, 0x3c800000, v218
	v_cmp_gt_f32_e32 vcc, s66, v3
	v_mul_f32_e32 v5, 0x4b800000, v3
	s_nop 0
	v_cndmask_b32_e32 v3, v3, v5, vcc
	v_rsq_f32_e32 v3, v3
	s_nop 0
	v_mul_f32_e32 v5, 0x45800000, v3
	v_cndmask_b32_e32 v3, v3, v5, vcc
	v_mul_f32_e32 v13, v20, v3
	v_or_b32_e32 v20, s60, v1
	v_mul_f32_e32 v15, v21, v3
	v_ashrrev_i32_e32 v21, 31, v20
	v_lshlrev_b64 v[20:21], 11, v[20:21]
	v_lshl_add_u64 v[20:21], s[20:21], 0, v[20:21]
	v_mul_f32_e32 v5, v16, v3
	v_mul_f32_e32 v7, v17, v3
	v_mul_f32_e32 v9, v18, v3
	v_mul_f32_e32 v11, v19, v3
	v_mul_f32_e32 v16, v22, v3
	v_mul_f32_e32 v3, v23, v3
	v_lshl_add_u64 v[20:21], v[20:21], 0, s[72:73]
	v_mul_f32_e32 v19, v12, v16
	v_mul_f32_e32 v3, v14, v3
	v_lshl_add_u64 v[20:21], v[20:21], 0, v[216:217]
	v_or_b32_e32 v1, 16, v32
	v_mul_f32_e32 v5, v0, v5
	v_mul_f32_e32 v7, v2, v7
	v_mul_f32_e32 v9, v4, v9
	v_mul_f32_e32 v11, v6, v11
	v_mul_f32_e32 v13, v8, v13
	v_mul_f32_e32 v15, v10, v15
	v_cvt_pk_bf16_f32 v16, v5, v7
	v_cvt_pk_bf16_f32 v17, v9, v11
	v_cvt_pk_bf16_f32 v18, v13, v15
	v_cvt_pk_bf16_f32 v19, v19, v3
	global_store_dwordx4 v[20:21], v[16:19], off offset:512
	v_lshl_add_u32 v3, v1, 8, v33
	ds_read_b128 v[16:19], v3
	ds_read_b128 v[20:23], v3 offset:16
	s_waitcnt lgkmcnt(1)
	v_pk_mul_f32 v[24:25], v[18:19], v[18:19]
	v_pk_mul_f32 v[26:27], v[16:17], v[16:17]
	s_nop 0
	v_pk_mov_b32 v[28:29], v[26:27], v[24:25] op_sel:[1,0]
	v_mov_b32_e32 v27, v25
	v_pk_add_f32 v[24:25], v[28:29], v[26:27]
	s_waitcnt lgkmcnt(0)
	v_pk_mul_f32 v[26:27], v[22:23], v[22:23]
	v_pk_mul_f32 v[28:29], v[20:21], v[20:21]
	v_mov_b32_e32 v30, v26
	v_mov_b32_e32 v31, v28
	v_mov_b32_e32 v28, v27
	v_pk_add_f32 v[26:27], v[30:31], v[28:29]
	v_add_f32_e32 v3, v24, v25
	v_add_f32_e32 v3, v3, v27
	v_add_f32_e32 v3, v26, v3
	s_nop 1
	v_add_f32_dpp v3, v3, v3 quad_perm:[1,0,3,2] row_mask:0xf bank_mask:0xf bound_ctrl:1
	s_nop 1
	v_add_f32_dpp v3, v3, v3 quad_perm:[2,3,0,1] row_mask:0xf bank_mask:0xf bound_ctrl:1
	s_nop 1
	v_add_f32_dpp v3, v3, v3 row_half_mirror row_mask:0xf bank_mask:0xf bound_ctrl:1
	v_fmamk_f32 v3, v3, 0x3c800000, v218
	v_cmp_gt_f32_e32 vcc, s66, v3
	v_mul_f32_e32 v5, 0x4b800000, v3
	s_nop 0
	v_cndmask_b32_e32 v3, v3, v5, vcc
	v_rsq_f32_e32 v3, v3
	s_nop 0
	v_mul_f32_e32 v5, 0x45800000, v3
	v_cndmask_b32_e32 v3, v3, v5, vcc
	v_mul_f32_e32 v13, v20, v3
	v_or_b32_e32 v20, s60, v1
	v_mul_f32_e32 v15, v21, v3
	v_ashrrev_i32_e32 v21, 31, v20
	v_lshlrev_b64 v[20:21], 11, v[20:21]
	v_mul_f32_e32 v5, v16, v3
	v_lshl_add_u64 v[20:21], s[20:21], 0, v[20:21]
	v_mul_f32_e32 v5, v0, v5
	v_mul_f32_e32 v7, v17, v3
	v_mul_f32_e32 v16, v22, v3
	v_lshl_add_u64 v[20:21], v[20:21], 0, s[72:73]
	v_mul_f32_e32 v7, v2, v7
	v_mul_f32_e32 v9, v18, v3
	v_mul_f32_e32 v11, v19, v3
	v_mul_f32_e32 v19, v12, v16
	v_mul_f32_e32 v3, v23, v3
	v_cvt_pk_bf16_f32 v16, v5, v7
	v_lshl_add_u64 v[20:21], v[20:21], 0, v[216:217]
	v_or_b32_e32 v5, 24, v32
	v_mul_f32_e32 v9, v4, v9
	v_mul_f32_e32 v11, v6, v11
	v_mul_f32_e32 v13, v8, v13
	v_mul_f32_e32 v15, v10, v15
	v_mul_f32_e32 v3, v14, v3
	v_cvt_pk_bf16_f32 v17, v9, v11
	v_cvt_pk_bf16_f32 v18, v13, v15
	v_cvt_pk_bf16_f32 v19, v19, v3
	global_store_dwordx4 v[20:21], v[16:19], off offset:512
	v_lshl_add_u32 v1, v5, 8, v33
	ds_read_b128 v[16:19], v1
	ds_read_b128 v[20:23], v1 offset:16
	s_waitcnt lgkmcnt(1)
	v_pk_mul_f32 v[24:25], v[18:19], v[18:19]
	v_pk_mul_f32 v[26:27], v[16:17], v[16:17]
	s_nop 0
	v_pk_mov_b32 v[28:29], v[26:27], v[24:25] op_sel:[1,0]
	v_mov_b32_e32 v27, v25
	v_pk_add_f32 v[24:25], v[28:29], v[26:27]
	s_waitcnt lgkmcnt(0)
	v_pk_mul_f32 v[26:27], v[22:23], v[22:23]
	v_pk_mul_f32 v[28:29], v[20:21], v[20:21]
	v_mov_b32_e32 v30, v26
	v_mov_b32_e32 v31, v28
	v_mov_b32_e32 v28, v27
	v_pk_add_f32 v[26:27], v[30:31], v[28:29]
	v_add_f32_e32 v1, v24, v25
	v_add_f32_e32 v1, v1, v27
	v_add_f32_e32 v1, v26, v1
	s_nop 1
	v_add_f32_dpp v1, v1, v1 quad_perm:[1,0,3,2] row_mask:0xf bank_mask:0xf bound_ctrl:1
	s_nop 1
	v_add_f32_dpp v1, v1, v1 quad_perm:[2,3,0,1] row_mask:0xf bank_mask:0xf bound_ctrl:1
	s_nop 1
	v_add_f32_dpp v1, v1, v1 row_half_mirror row_mask:0xf bank_mask:0xf bound_ctrl:1
	v_fmamk_f32 v1, v1, 0x3c800000, v218
	v_cmp_gt_f32_e32 vcc, s66, v1
	v_mul_f32_e32 v3, 0x4b800000, v1
	s_nop 0
	v_cndmask_b32_e32 v1, v1, v3, vcc
	v_rsq_f32_e32 v1, v1
	s_nop 0
	v_mul_f32_e32 v3, 0x45800000, v1
	v_cndmask_b32_e32 v1, v1, v3, vcc
	v_mul_f32_e32 v3, v16, v1
	v_mul_f32_e32 v0, v0, v3
	v_mul_f32_e32 v3, v17, v1
	v_mul_f32_e32 v2, v2, v3
	v_mul_f32_e32 v3, v18, v1
	v_mul_f32_e32 v3, v4, v3
	v_mul_f32_e32 v4, v19, v1
	v_mul_f32_e32 v4, v6, v4
	v_mul_f32_e32 v6, v20, v1
	v_mul_f32_e32 v6, v8, v6
	v_mul_f32_e32 v7, v21, v1
	v_mul_f32_e32 v8, v22, v1
	v_mul_f32_e32 v1, v23, v1
	v_mul_f32_e32 v9, v14, v1
	v_cvt_pk_bf16_f32 v0, v0, v2
	v_cvt_pk_bf16_f32 v1, v3, v4
	v_or_b32_e32 v4, s60, v5
	v_ashrrev_i32_e32 v5, 31, v4
	v_lshlrev_b64 v[4:5], 11, v[4:5]
	v_lshl_add_u64 v[4:5], s[20:21], 0, v[4:5]
	v_lshl_add_u64 v[4:5], v[4:5], 0, s[72:73]
	v_lshl_add_u64 v[4:5], v[4:5], 0, v[216:217]
	v_mul_f32_e32 v7, v10, v7
	v_mul_f32_e32 v8, v12, v8
	v_cvt_pk_bf16_f32 v2, v6, v7
	v_cvt_pk_bf16_f32 v3, v8, v9
	global_store_dwordx4 v[4:5], v[0:3], off offset:512
	s_branch .Lat_afterA
